# half of the XCDs enter P5 ~7us late (skew kept by XCD-local barriers) to interleave epilogue store bursts
# baseline (speedup 1.0000x reference)
;     __device__ bool next(int i, Unit& u) const {
;         const long L = (long)i * G + c; if (L >= nwg) return false;
;         int wgid = (int)L; { const int q = nwg / NXCD, r = nwg % NXCD, xcd = wgid % NXCD, off = wgid / NXCD; wgid = (xcd < r ? xcd * (q + 1) : r * (q + 1) + (xcd - r) * q) + off; }
; __global__ void __launch_bounds__(NTHR, 2) fwd_megakernel(Args a) {
;     ...
;         pg8::Gemm g{H, WoT, M, DM, DM}; pg8::StaticOrderW<4> S; S.init(M, DM, G, blk);
;         pg8::EpiRes3 E{x, out, mod, g2, H2, part};
;         pg8::gemm_phase<pg8::EpiRes3, pg8::StaticOrderW<4>, true, true>(lds, g, S, E);
.LBB0_663:
	s_or_b64 exec, exec, s[2:3]
	v_readfirstlane_b32 s98, v237
	s_and_b32 s98, s98, 4
	s_cmp_eq_u32 s98, 0
	s_cbranch_scc1 .Lskew_skip
	s_sleep 127
	s_sleep 127
.Lskew_skip:
	v_readlane_b32 s4, v235, 7
	v_readlane_b32 s5, v235, 8
	s_mov_b64 s[2:3], -1
	s_and_b64 vcc, exec, s[4:5]
	s_waitcnt lgkmcnt(0)
	s_barrier
	s_cbranch_vccz .LBB0_874
	v_mov_b32_e32 v8, v186
	s_and_b64 vcc, exec, s[0:1]
	v_readfirstlane_b32 s5, v8
	s_cbranch_vccnz .LBB0_688
	s_ashr_i32 s33, s62, 31
	s_lshr_b32 s2, s33, 29
	s_add_i32 s6, s62, s2
	s_and_b32 s2, s6, -8
	s_sub_i32 s7, s62, s2
	s_cmp_gt_i32 s7, -1
	s_cbranch_scc0 .LBB0_667
	s_lshl_b32 s4, s7, 6
	s_cbranch_execz .LBB0_668
	s_branch .LBB0_669
